# plus attention unit epilogue: 16 subln gain loads issued up front, counted waits
# baseline (speedup 1.0000x reference)
; __device__ __forceinline__ void dattn_unit(LAS unsigned char* lds, int b, int h, int qb, const bf16* Q, const bf16* K, const bf16* V, bf16* YB, float lam, const float* subg, float oml, int tid) {
;     ...
;     const float l1 = lsum[0] + __shfl_xor(lsum[0], 32), l2 = lsum[1] + __shfl_xor(lsum[1], 32);
;     const float i1 = 1.0f / l1, i2 = lam / l2; float ss = 0.f;
; #pragma unroll
;     for (int cb = 0; cb < 4; ++cb)
; #pragma unroll
;         for (int r = 0; r < 16; ++r) { const float y = o[0][cb][r] * i1 - o[1][cb][r] * i2; o[0][cb][r] = y; ss += y * y; }
.LBB0_219:
	v_cmp_lt_i32_e32 vcc, v252, v246
	s_nop 3
	v_mov_b32_e32 v135, v98
	v_mov_b32_e32 v98, v97
	v_cndmask_b32_e32 v128, v245, v252, vcc
	v_lshlrev_b32_e32 v139, 2, v128
	ds_bpermute_b32 v128, v139, v179
	ds_bpermute_b32 v129, v139, v181
	s_waitcnt lgkmcnt(0)
	s_barrier
	v_add_f32_e32 v128, v179, v128
	v_div_scale_f32 v130, s[46:47], v128, v128, 1.0
	v_rcp_f32_e32 v131, v130
	v_add_f32_e32 v129, v181, v129
	v_lshlrev_b32_e32 v208, 1, v160
	s_add_i32 s55, s55, 1
	v_fma_f32 v132, -v130, v131, 1.0
	v_fmac_f32_e32 v131, v132, v131
	v_div_scale_f32 v132, vcc, 1.0, v128, 1.0
	v_mul_f32_e32 v133, v132, v131
	v_fma_f32 v134, -v130, v133, v132
	v_fmac_f32_e32 v133, v134, v131
	v_fma_f32 v130, -v130, v133, v132
	v_div_fmas_f32 v130, v130, v131, v133
	v_div_fixup_f32 v136, v130, v128, 1.0
	v_div_scale_f32 v128, s[46:47], v129, v129, v186
	v_rcp_f32_e32 v130, v128
	v_mov_b32_e32 v134, v96
	s_cmp_lg_u32 s55, 4
	v_fma_f32 v131, -v128, v130, 1.0
	v_fmac_f32_e32 v130, v131, v130
	v_div_scale_f32 v131, vcc, v186, v129, v186
	v_mul_f32_e32 v132, v131, v130
	v_fma_f32 v133, -v128, v132, v131
	v_fmac_f32_e32 v132, v133, v130
	v_fma_f32 v128, -v128, v132, v131
	v_div_fmas_f32 v128, v128, v130, v132
	v_div_fixup_f32 v138, v128, v129, v186
	v_pk_mul_f32 v[12:13], v[12:13], v[138:139] op_sel_hi:[1,0]
	v_mov_b32_e32 v129, v114
	v_pk_fma_f32 v[28:29], v[28:29], v[136:137], v[12:13] op_sel_hi:[1,0,1] neg_lo:[0,0,1] neg_hi:[0,0,1]
	v_pk_mul_f32 v[12:13], v[14:15], v[138:139] op_sel_hi:[1,0]
	v_mov_b32_e32 v114, v113
	v_pk_fma_f32 v[30:31], v[30:31], v[136:137], v[12:13] op_sel_hi:[1,0,1] neg_lo:[0,0,1] neg_hi:[0,0,1]
	v_lshlrev_b32_e32 v137, 2, v160
	v_pk_mul_f32 v[96:97], v[98:99], v[138:139] op_sel_hi:[1,0]
	v_mov_b32_e32 v98, v100
	v_mov_b32_e32 v99, v102
	v_mov_b32_e32 v128, v112
	v_pk_mul_f32 v[134:135], v[134:135], v[138:139] op_sel_hi:[1,0]
	v_pk_fma_f32 v[112:113], v[114:115], v[136:137], v[96:97] op_sel_hi:[1,0,1] neg_lo:[0,0,1] neg_hi:[0,0,1]
	v_mov_b32_e32 v96, v116
	v_mov_b32_e32 v97, v118
	v_pk_mul_f32 v[98:99], v[98:99], v[138:139] op_sel_hi:[1,0]
	v_mov_b32_e32 v102, v101
	v_pk_fma_f32 v[128:129], v[128:129], v[136:137], v[134:135] op_sel_hi:[1,0,1] neg_lo:[0,0,1] neg_hi:[0,0,1]
	v_pk_fma_f32 v[134:135], v[96:97], v[136:137], v[98:99] op_sel_hi:[1,0,1] neg_lo:[0,0,1] neg_hi:[0,0,1]
	v_mov_b32_e32 v118, v117
	v_pk_mul_f32 v[96:97], v[102:103], v[138:139] op_sel_hi:[1,0]
	v_mov_b32_e32 v98, v104
	v_mov_b32_e32 v99, v106
	v_pk_fma_f32 v[118:119], v[118:119], v[136:137], v[96:97] op_sel_hi:[1,0,1] neg_lo:[0,0,1] neg_hi:[0,0,1]
	v_mov_b32_e32 v96, v120
	v_mov_b32_e32 v97, v122
	v_pk_mul_f32 v[98:99], v[98:99], v[138:139] op_sel_hi:[1,0]
	v_mov_b32_e32 v106, v105
	v_pk_fma_f32 v[116:117], v[96:97], v[136:137], v[98:99] op_sel_hi:[1,0,1] neg_lo:[0,0,1] neg_hi:[0,0,1]
	v_mov_b32_e32 v122, v121
	v_pk_mul_f32 v[96:97], v[106:107], v[138:139] op_sel_hi:[1,0]
	v_mov_b32_e32 v98, v108
	v_mov_b32_e32 v99, v110
	v_pk_fma_f32 v[106:107], v[122:123], v[136:137], v[96:97] op_sel_hi:[1,0,1] neg_lo:[0,0,1] neg_hi:[0,0,1]
	v_mov_b32_e32 v96, v124
	v_mov_b32_e32 v97, v126
	v_pk_mul_f32 v[98:99], v[98:99], v[138:139] op_sel_hi:[1,0]
	v_mov_b32_e32 v110, v109
	v_pk_fma_f32 v[102:103], v[96:97], v[136:137], v[98:99] op_sel_hi:[1,0,1] neg_lo:[0,0,1] neg_hi:[0,0,1]
	v_mov_b32_e32 v126, v125
	v_pk_mul_f32 v[96:97], v[110:111], v[138:139] op_sel_hi:[1,0]
	v_mov_b32_e32 v98, v64
	v_mov_b32_e32 v99, v66
	v_mov_b32_e32 v66, v65
	v_pk_fma_f32 v[104:105], v[126:127], v[136:137], v[96:97] op_sel_hi:[1,0,1] neg_lo:[0,0,1] neg_hi:[0,0,1]
	v_mov_b32_e32 v96, v80
	v_mov_b32_e32 v97, v82
	v_pk_mul_f32 v[98:99], v[98:99], v[138:139] op_sel_hi:[1,0]
	v_mov_b32_e32 v82, v81
	v_pk_mul_f32 v[64:65], v[66:67], v[138:139] op_sel_hi:[1,0]
	v_mov_b32_e32 v66, v68
	v_mov_b32_e32 v67, v70
	v_pk_fma_f32 v[100:101], v[96:97], v[136:137], v[98:99] op_sel_hi:[1,0,1] neg_lo:[0,0,1] neg_hi:[0,0,1]
	v_pk_fma_f32 v[98:99], v[82:83], v[136:137], v[64:65] op_sel_hi:[1,0,1] neg_lo:[0,0,1] neg_hi:[0,0,1]
	v_mov_b32_e32 v64, v84
	v_mov_b32_e32 v65, v86
	v_pk_mul_f32 v[66:67], v[66:67], v[138:139] op_sel_hi:[1,0]
	v_mov_b32_e32 v70, v69
	v_pk_fma_f32 v[96:97], v[64:65], v[136:137], v[66:67] op_sel_hi:[1,0,1] neg_lo:[0,0,1] neg_hi:[0,0,1]
	v_mov_b32_e32 v86, v85
	v_pk_mul_f32 v[64:65], v[70:71], v[138:139] op_sel_hi:[1,0]
	v_mov_b32_e32 v66, v72
	v_mov_b32_e32 v67, v74
	v_pk_fma_f32 v[82:83], v[86:87], v[136:137], v[64:65] op_sel_hi:[1,0,1] neg_lo:[0,0,1] neg_hi:[0,0,1]
	v_mov_b32_e32 v64, v88
	v_mov_b32_e32 v65, v90
	v_pk_mul_f32 v[66:67], v[66:67], v[138:139] op_sel_hi:[1,0]
	v_mov_b32_e32 v74, v73
	v_pk_fma_f32 v[80:81], v[64:65], v[136:137], v[66:67] op_sel_hi:[1,0,1] neg_lo:[0,0,1] neg_hi:[0,0,1]
	v_mov_b32_e32 v90, v89
	v_pk_mul_f32 v[64:65], v[74:75], v[138:139] op_sel_hi:[1,0]
	v_mov_b32_e32 v66, v76
	v_mov_b32_e32 v67, v78
	v_pk_fma_f32 v[74:75], v[90:91], v[136:137], v[64:65] op_sel_hi:[1,0,1] neg_lo:[0,0,1] neg_hi:[0,0,1]
	v_mov_b32_e32 v64, v92
	v_mov_b32_e32 v65, v94
	v_pk_mul_f32 v[66:67], v[66:67], v[138:139] op_sel_hi:[1,0]
	v_mov_b32_e32 v78, v77
	v_pk_fma_f32 v[72:73], v[64:65], v[136:137], v[66:67] op_sel_hi:[1,0,1] neg_lo:[0,0,1] neg_hi:[0,0,1]
	v_mov_b32_e32 v94, v93
	v_pk_mul_f32 v[64:65], v[78:79], v[138:139] op_sel_hi:[1,0]
	v_mov_b32_e32 v66, v32
	v_mov_b32_e32 v67, v34
	v_mov_b32_e32 v34, v33
	v_pk_fma_f32 v[70:71], v[94:95], v[136:137], v[64:65] op_sel_hi:[1,0,1] neg_lo:[0,0,1] neg_hi:[0,0,1]
	v_mov_b32_e32 v64, v48
	v_mov_b32_e32 v65, v50
	v_pk_mul_f32 v[66:67], v[66:67], v[138:139] op_sel_hi:[1,0]
	v_mov_b32_e32 v50, v49
	v_pk_mul_f32 v[32:33], v[34:35], v[138:139] op_sel_hi:[1,0]
; __device__ __forceinline__ void dattn_unit(LAS unsigned char* lds, int b, int h, int qb, const bf16* Q, const bf16* K, const bf16* V, bf16* YB, float lam, const float* subg, float oml, int tid) {
;     ...
;         for (int r = 0; r < 16; ++r) { const float y = o[0][cb][r] * i1 - o[1][cb][r] * i2; o[0][cb][r] = y; ss += y * y; }
;     ss += __shfl_xor(ss, 32);
;     const float rstd = rsqrtf(ss * (1.f / 128.f) + EPS) * oml;
;     bf16* op = YB + (rowb + q) * 1024 + h * 128;
; #pragma unroll
;     for (int cb = 0; cb < 4; ++cb)
; #pragma unroll
;         for (int rg = 0; rg < 4; ++rg) { const int c = 32 * cb + 8 * rg + 4 * hi; const f32x4 g = *(const f32x4*)(subg + c);
	v_mov_b32_e32 v34, v36
	v_mov_b32_e32 v35, v38
	v_pk_fma_f32 v[68:69], v[64:65], v[136:137], v[66:67] op_sel_hi:[1,0,1] neg_lo:[0,0,1] neg_hi:[0,0,1]
	v_pk_fma_f32 v[66:67], v[50:51], v[136:137], v[32:33] op_sel_hi:[1,0,1] neg_lo:[0,0,1] neg_hi:[0,0,1]
	v_mov_b32_e32 v32, v52
	v_mov_b32_e32 v33, v54
	v_pk_mul_f32 v[34:35], v[34:35], v[138:139] op_sel_hi:[1,0]
	v_mov_b32_e32 v38, v37
	v_pk_fma_f32 v[64:65], v[32:33], v[136:137], v[34:35] op_sel_hi:[1,0,1] neg_lo:[0,0,1] neg_hi:[0,0,1]
	v_mov_b32_e32 v54, v53
	v_pk_mul_f32 v[32:33], v[38:39], v[138:139] op_sel_hi:[1,0]
	v_mov_b32_e32 v34, v40
	v_mov_b32_e32 v35, v42
	v_pk_fma_f32 v[50:51], v[54:55], v[136:137], v[32:33] op_sel_hi:[1,0,1] neg_lo:[0,0,1] neg_hi:[0,0,1]
	v_mov_b32_e32 v32, v56
	v_mov_b32_e32 v33, v58
	v_pk_mul_f32 v[34:35], v[34:35], v[138:139] op_sel_hi:[1,0]
	v_mov_b32_e32 v42, v41
	v_pk_fma_f32 v[48:49], v[32:33], v[136:137], v[34:35] op_sel_hi:[1,0,1] neg_lo:[0,0,1] neg_hi:[0,0,1]
	v_mov_b32_e32 v58, v57
	v_pk_mul_f32 v[32:33], v[42:43], v[138:139] op_sel_hi:[1,0]
	v_mov_b32_e32 v34, v44
	v_mov_b32_e32 v35, v46
	v_pk_fma_f32 v[38:39], v[58:59], v[136:137], v[32:33] op_sel_hi:[1,0,1] neg_lo:[0,0,1] neg_hi:[0,0,1]
	v_mov_b32_e32 v32, v60
	v_mov_b32_e32 v33, v62
	v_pk_mul_f32 v[34:35], v[34:35], v[138:139] op_sel_hi:[1,0]
	v_mov_b32_e32 v46, v45
	v_pk_fma_f32 v[36:37], v[32:33], v[136:137], v[34:35] op_sel_hi:[1,0,1] neg_lo:[0,0,1] neg_hi:[0,0,1]
	v_mov_b32_e32 v62, v61
	v_pk_mul_f32 v[32:33], v[46:47], v[138:139] op_sel_hi:[1,0]
	v_mov_b32_e32 v47, v2
	v_mov_b32_e32 v2, v1
	global_load_dwordx4 v[12:15], v137, s[4:5]
	global_load_dwordx4 v[212:215], v137, s[4:5] offset:32
	global_load_dwordx4 v[216:219], v137, s[4:5] offset:64
	global_load_dwordx4 v[220:223], v137, s[4:5] offset:96
	global_load_dwordx4 v[224:227], v137, s[4:5] offset:128
	global_load_dwordx4 v[228:231], v137, s[4:5] offset:160
	global_load_dwordx4 v[232:235], v137, s[4:5] offset:192
	global_load_dwordx4 v[236:239], v137, s[4:5] offset:224
	global_load_dwordx4 v[240:243], v137, s[4:5] offset:256
	global_load_dwordx4 v[192:195], v137, s[4:5] offset:288
	global_load_dwordx4 v[196:199], v137, s[4:5] offset:320
	global_load_dwordx4 v[200:203], v137, s[4:5] offset:352
	global_load_dwordx4 v[204:207], v137, s[4:5] offset:384
	global_load_dwordx4 v[164:167], v137, s[4:5] offset:416
	global_load_dwordx4 v[168:171], v137, s[4:5] offset:448
	global_load_dwordx4 v[172:175], v137, s[4:5] offset:480
	v_pk_mul_f32 v[140:141], v[128:129], v[128:129]
	v_pk_mul_f32 v[142:143], v[112:113], v[112:113]
	v_pk_fma_f32 v[34:35], v[62:63], v[136:137], v[32:33] op_sel_hi:[1,0,1] neg_lo:[0,0,1] neg_hi:[0,0,1]
	v_mov_b32_e32 v33, v18
	v_mov_b32_e32 v46, v0
	v_mov_b32_e32 v18, v17
	v_pk_mul_f32 v[0:1], v[2:3], v[138:139] op_sel_hi:[1,0]
	v_pk_mul_f32 v[144:145], v[134:135], v[134:135]
	v_pk_fma_f32 v[18:19], v[18:19], v[136:137], v[0:1] op_sel_hi:[1,0,1] neg_lo:[0,0,1] neg_hi:[0,0,1]
	v_mov_b32_e32 v0, v20
	v_add_f32_e32 v20, v140, v142
	v_add_f32_e32 v20, v141, v20
	v_add_f32_e32 v20, v143, v20
	v_pk_mul_f32 v[146:147], v[118:119], v[118:119]
	v_add_f32_e32 v20, v144, v20
	v_add_f32_e32 v20, v146, v20
	v_add_f32_e32 v20, v145, v20
	v_pk_mul_f32 v[148:149], v[116:117], v[116:117]
	v_add_f32_e32 v20, v147, v20
	v_pk_mul_f32 v[120:121], v[106:107], v[106:107]
	v_add_f32_e32 v20, v148, v20
	v_add_f32_e32 v20, v120, v20
	v_add_f32_e32 v20, v149, v20
	v_pk_mul_f32 v[122:123], v[102:103], v[102:103]
	v_add_f32_e32 v20, v121, v20
	v_pk_mul_f32 v[108:109], v[104:105], v[104:105]
	v_add_f32_e32 v20, v122, v20
	v_add_f32_e32 v20, v108, v20
	v_add_f32_e32 v20, v123, v20
	v_pk_mul_f32 v[110:111], v[100:101], v[100:101]
	v_add_f32_e32 v20, v109, v20
	v_pk_mul_f32 v[124:125], v[98:99], v[98:99]
	v_add_f32_e32 v20, v110, v20
	v_add_f32_e32 v20, v124, v20
	v_add_f32_e32 v20, v111, v20
	v_pk_mul_f32 v[126:127], v[96:97], v[96:97]
	v_add_f32_e32 v20, v125, v20
	v_pk_mul_f32 v[84:85], v[82:83], v[82:83]
	v_add_f32_e32 v20, v126, v20
	v_add_f32_e32 v20, v84, v20
	v_add_f32_e32 v20, v127, v20
	v_pk_mul_f32 v[86:87], v[80:81], v[80:81]
	v_add_f32_e32 v20, v85, v20
	v_pk_mul_f32 v[88:89], v[74:75], v[74:75]
	v_add_f32_e32 v20, v86, v20
	v_add_f32_e32 v20, v88, v20
	v_add_f32_e32 v20, v87, v20
	v_pk_mul_f32 v[90:91], v[72:73], v[72:73]
	v_add_f32_e32 v20, v89, v20
	v_pk_mul_f32 v[76:77], v[70:71], v[70:71]
	v_add_f32_e32 v20, v90, v20
	v_add_f32_e32 v20, v76, v20
	v_add_f32_e32 v20, v91, v20
	v_pk_mul_f32 v[78:79], v[68:69], v[68:69]
	v_add_f32_e32 v20, v77, v20
	v_pk_mul_f32 v[92:93], v[66:67], v[66:67]
	v_add_f32_e32 v20, v78, v20
	v_add_f32_e32 v20, v92, v20
	v_add_f32_e32 v20, v79, v20
	v_pk_mul_f32 v[94:95], v[64:65], v[64:65]
	v_add_f32_e32 v20, v93, v20
	v_pk_mul_f32 v[52:53], v[50:51], v[50:51]
	v_add_f32_e32 v20, v94, v20
	v_add_f32_e32 v20, v52, v20
	v_add_f32_e32 v20, v95, v20
	v_pk_mul_f32 v[54:55], v[48:49], v[48:49]
	v_add_f32_e32 v20, v53, v20
	v_pk_mul_f32 v[40:41], v[38:39], v[38:39]
	v_add_f32_e32 v20, v54, v20
	v_add_f32_e32 v20, v40, v20
	v_add_f32_e32 v20, v55, v20
	v_pk_mul_f32 v[42:43], v[36:37], v[36:37]
	v_add_f32_e32 v20, v41, v20
	v_pk_mul_f32 v[44:45], v[34:35], v[34:35]
	v_add_f32_e32 v20, v42, v20
	v_mov_b32_e32 v32, v16
	v_pk_mul_f32 v[46:47], v[46:47], v[138:139] op_sel_hi:[1,0]
	v_add_f32_e32 v20, v44, v20
	v_pk_fma_f32 v[32:33], v[32:33], v[136:137], v[46:47] op_sel_hi:[1,0,1] neg_lo:[0,0,1] neg_hi:[0,0,1]
	v_mov_b32_e32 v2, v4
	v_mov_b32_e32 v3, v6
	v_add_f32_e32 v20, v43, v20
	v_pk_mul_f32 v[46:47], v[32:33], v[32:33]
	v_mov_b32_e32 v1, v22
	v_pk_mul_f32 v[2:3], v[2:3], v[138:139] op_sel_hi:[1,0]
	v_mov_b32_e32 v6, v5
; __device__ __forceinline__ unsigned pk2(float lo, float hi) { return f2bf(lo) | (f2bf(hi) << 16); }
; __device__ __forceinline__ void dattn_unit(LAS unsigned char* lds, int b, int h, int qb, const bf16* Q, const bf16* K, const bf16* V, bf16* YB, float lam, const float* subg, float oml, int tid) {
;     ...
;     ss += __shfl_xor(ss, 32);
;     const float rstd = rsqrtf(ss * (1.f / 128.f) + EPS) * oml;
;     bf16* op = YB + (rowb + q) * 1024 + h * 128;
; #pragma unroll
;     for (int cb = 0; cb < 4; ++cb)
; #pragma unroll
;         for (int rg = 0; rg < 4; ++rg) { const int c = 32 * cb + 8 * rg + 4 * hi; const f32x4 g = *(const f32x4*)(subg + c);
;             v2u wv; wv.x = pk2(o[0][cb][4 * rg + 0] * rstd * g.x, o[0][cb][4 * rg + 1] * rstd * g.y); wv.y = pk2(o[0][cb][4 * rg + 2] * rstd * g.z, o[0][cb][4 * rg + 3] * rstd * g.w);
;             *(v2u*)(op + c) = wv; }
	v_add_f32_e32 v20, v45, v20
	v_pk_mul_f32 v[56:57], v[18:19], v[18:19]
	v_pk_fma_f32 v[16:17], v[0:1], v[136:137], v[2:3] op_sel_hi:[1,0,1] neg_lo:[0,0,1] neg_hi:[0,0,1]
	v_mov_b32_e32 v22, v21
	v_pk_mul_f32 v[0:1], v[6:7], v[138:139] op_sel_hi:[1,0]
	v_add_f32_e32 v20, v46, v20
	v_pk_fma_f32 v[4:5], v[22:23], v[136:137], v[0:1] op_sel_hi:[1,0,1] neg_lo:[0,0,1] neg_hi:[0,0,1]
	v_add_f32_e32 v20, v56, v20
	v_mov_b32_e32 v0, v5
	v_mov_b32_e32 v1, v17
	v_mov_b32_e32 v2, v8
	v_mov_b32_e32 v3, v10
	v_add_f32_e32 v20, v47, v20
	v_pk_mul_f32 v[6:7], v[0:1], v[0:1]
	v_mov_b32_e32 v0, v24
	v_mov_b32_e32 v1, v26
	v_pk_mul_f32 v[2:3], v[2:3], v[138:139] op_sel_hi:[1,0]
	v_mov_b32_e32 v10, v9
	v_add_f32_e32 v20, v57, v20
	v_pk_fma_f32 v[2:3], v[0:1], v[136:137], v[2:3] op_sel_hi:[1,0,1] neg_lo:[0,0,1] neg_hi:[0,0,1]
	v_mov_b32_e32 v26, v25
	v_pk_mul_f32 v[0:1], v[10:11], v[138:139] op_sel_hi:[1,0]
	v_fmac_f32_e32 v20, v16, v16
	v_pk_fma_f32 v[0:1], v[26:27], v[136:137], v[0:1] op_sel_hi:[1,0,1] neg_lo:[0,0,1] neg_hi:[0,0,1]
	v_fmac_f32_e32 v20, v4, v4
	v_mov_b32_e32 v8, v0
	v_mov_b32_e32 v9, v2
	v_add_f32_e32 v7, v7, v20
	v_pk_mul_f32 v[8:9], v[8:9], v[8:9]
	v_add_f32_e32 v6, v6, v7
	v_mov_b32_e32 v10, v1
	v_mov_b32_e32 v11, v3
	v_add_f32_e32 v6, v9, v6
	v_pk_mul_f32 v[10:11], v[10:11], v[10:11]
	v_add_f32_e32 v6, v8, v6
	v_add_f32_e32 v6, v11, v6
	v_pk_mul_f32 v[130:131], v[28:29], v[28:29]
	v_add_f32_e32 v6, v10, v6
	v_add_f32_e32 v6, v130, v6
	v_pk_mul_f32 v[132:133], v[30:31], v[30:31]
	v_add_f32_e32 v6, v131, v6
	v_add_f32_e32 v6, v132, v6
	v_add_f32_e32 v6, v133, v6
	ds_bpermute_b32 v7, v139, v6
	s_waitcnt vmcnt(15)
	v_mov_b32_e32 v114, v12
	v_mov_b32_e32 v115, v14
	v_mov_b32_e32 v14, v13
	v_lshl_add_u64 v[12:13], v[176:177], 0, v[208:209]
	s_waitcnt lgkmcnt(0)
	v_add_f32_e32 v6, v6, v7
	v_fmamk_f32 v6, v6, 0x3c000000, v210
	v_cmp_gt_f32_e32 vcc, s39, v6
	v_mul_f32_e32 v7, 0x4b800000, v6
	s_nop 0
	v_cndmask_b32_e32 v6, v6, v7, vcc
	v_rsq_f32_e32 v6, v6
	s_nop 0
	v_mul_f32_e32 v7, 0x45800000, v6
	v_cndmask_b32_e32 v6, v6, v7, vcc
	v_mul_f32_e32 v6, v187, v6
	v_pk_mul_f32 v[8:9], v[128:129], v[6:7] op_sel_hi:[1,0]
	v_pk_mul_f32 v[10:11], v[112:113], v[6:7] op_sel_hi:[1,0]
	v_pk_mul_f32 v[8:9], v[114:115], v[8:9]
	v_pk_mul_f32 v[10:11], v[14:15], v[10:11]
	v_and_b32_sdwa v7, v9, v244 dst_sel:DWORD dst_unused:UNUSED_PAD src0_sel:WORD_1 src1_sel:DWORD
	v_and_b32_sdwa v14, v8, v244 dst_sel:DWORD dst_unused:UNUSED_PAD src0_sel:WORD_1 src1_sel:DWORD
	v_add3_u32 v8, v8, v14, s33
	v_add3_u32 v7, v9, v7, s33
	v_and_b32_sdwa v9, v11, v244 dst_sel:DWORD dst_unused:UNUSED_PAD src0_sel:WORD_1 src1_sel:DWORD
	v_and_b32_sdwa v14, v10, v244 dst_sel:DWORD dst_unused:UNUSED_PAD src0_sel:WORD_1 src1_sel:DWORD
	v_add3_u32 v9, v11, v9, s33
	v_add3_u32 v10, v10, v14, s33
	v_and_b32_e32 v9, 0xffff0000, v9
	v_and_b32_e32 v10, 0xffff0000, v10
	v_or_b32_sdwa v9, v9, v7 dst_sel:DWORD dst_unused:UNUSED_PAD src0_sel:DWORD src1_sel:WORD_1
	v_or_b32_sdwa v8, v10, v8 dst_sel:DWORD dst_unused:UNUSED_PAD src0_sel:DWORD src1_sel:WORD_1
	global_store_dwordx2 v[12:13], v[8:9], off
	v_pk_mul_f32 v[14:15], v[134:135], v[6:7] op_sel_hi:[1,0]
	s_waitcnt vmcnt(15)
	v_mov_b32_e32 v8, v212
	v_mov_b32_e32 v9, v213
	v_mov_b32_e32 v10, v214
	v_mov_b32_e32 v11, v215
	v_mov_b32_e32 v20, v8
	v_mov_b32_e32 v21, v10
	v_pk_mul_f32 v[14:15], v[20:21], v[14:15]
	v_pk_mul_f32 v[20:21], v[118:119], v[6:7] op_sel_hi:[1,0]
	v_mov_b32_e32 v10, v9
	v_pk_mul_f32 v[8:9], v[10:11], v[20:21]
	v_and_b32_sdwa v10, v14, v244 dst_sel:DWORD dst_unused:UNUSED_PAD src0_sel:WORD_1 src1_sel:DWORD
	v_add3_u32 v10, v14, v10, s33
	v_and_b32_sdwa v11, v9, v244 dst_sel:DWORD dst_unused:UNUSED_PAD src0_sel:WORD_1 src1_sel:DWORD
	v_and_b32_sdwa v14, v8, v244 dst_sel:DWORD dst_unused:UNUSED_PAD src0_sel:WORD_1 src1_sel:DWORD
	v_and_b32_sdwa v7, v15, v244 dst_sel:DWORD dst_unused:UNUSED_PAD src0_sel:WORD_1 src1_sel:DWORD
	v_add3_u32 v9, v9, v11, s33
	v_add3_u32 v8, v8, v14, s33
	v_add3_u32 v7, v15, v7, s33
	v_and_b32_e32 v9, 0xffff0000, v9
	v_and_b32_e32 v8, 0xffff0000, v8
	v_or_b32_sdwa v9, v9, v7 dst_sel:DWORD dst_unused:UNUSED_PAD src0_sel:DWORD src1_sel:WORD_1
	v_or_b32_sdwa v8, v8, v10 dst_sel:DWORD dst_unused:UNUSED_PAD src0_sel:DWORD src1_sel:WORD_1
	global_store_dwordx2 v[12:13], v[8:9], off offset:16
	v_pk_mul_f32 v[14:15], v[116:117], v[6:7] op_sel_hi:[1,0]
	s_waitcnt vmcnt(15)
	v_mov_b32_e32 v8, v216
	v_mov_b32_e32 v9, v217
	v_mov_b32_e32 v10, v218
	v_mov_b32_e32 v11, v219
	v_mov_b32_e32 v20, v8
	v_mov_b32_e32 v21, v10
	v_pk_mul_f32 v[14:15], v[20:21], v[14:15]
	v_pk_mul_f32 v[20:21], v[106:107], v[6:7] op_sel_hi:[1,0]
	v_mov_b32_e32 v10, v9
	v_pk_mul_f32 v[8:9], v[10:11], v[20:21]
	v_and_b32_sdwa v10, v14, v244 dst_sel:DWORD dst_unused:UNUSED_PAD src0_sel:WORD_1 src1_sel:DWORD
	v_add3_u32 v10, v14, v10, s33
	v_and_b32_sdwa v11, v9, v244 dst_sel:DWORD dst_unused:UNUSED_PAD src0_sel:WORD_1 src1_sel:DWORD
	v_and_b32_sdwa v14, v8, v244 dst_sel:DWORD dst_unused:UNUSED_PAD src0_sel:WORD_1 src1_sel:DWORD
	v_and_b32_sdwa v7, v15, v244 dst_sel:DWORD dst_unused:UNUSED_PAD src0_sel:WORD_1 src1_sel:DWORD
	v_add3_u32 v9, v9, v11, s33
	v_add3_u32 v8, v8, v14, s33
	v_add3_u32 v7, v15, v7, s33
	v_and_b32_e32 v9, 0xffff0000, v9
	v_and_b32_e32 v8, 0xffff0000, v8
	v_or_b32_sdwa v9, v9, v7 dst_sel:DWORD dst_unused:UNUSED_PAD src0_sel:DWORD src1_sel:WORD_1
	v_or_b32_sdwa v8, v8, v10 dst_sel:DWORD dst_unused:UNUSED_PAD src0_sel:DWORD src1_sel:WORD_1
	global_store_dwordx2 v[12:13], v[8:9], off offset:32
	v_pk_mul_f32 v[14:15], v[102:103], v[6:7] op_sel_hi:[1,0]
	s_waitcnt vmcnt(15)
; __device__ __forceinline__ unsigned pk2(float lo, float hi) { return f2bf(lo) | (f2bf(hi) << 16); }
; __device__ __forceinline__ void dattn_unit(LAS unsigned char* lds, int b, int h, int qb, const bf16* Q, const bf16* K, const bf16* V, bf16* YB, float lam, const float* subg, float oml, int tid) {
;     ...
;     for (int cb = 0; cb < 4; ++cb)
; #pragma unroll
;         for (int rg = 0; rg < 4; ++rg) { const int c = 32 * cb + 8 * rg + 4 * hi; const f32x4 g = *(const f32x4*)(subg + c);
;             v2u wv; wv.x = pk2(o[0][cb][4 * rg + 0] * rstd * g.x, o[0][cb][4 * rg + 1] * rstd * g.y); wv.y = pk2(o[0][cb][4 * rg + 2] * rstd * g.z, o[0][cb][4 * rg + 3] * rstd * g.w);
;             *(v2u*)(op + c) = wv; }
	v_mov_b32_e32 v8, v220
	v_mov_b32_e32 v9, v221
	v_mov_b32_e32 v10, v222
	v_mov_b32_e32 v11, v223
	v_mov_b32_e32 v20, v8
	v_mov_b32_e32 v21, v10
	v_pk_mul_f32 v[14:15], v[20:21], v[14:15]
	v_pk_mul_f32 v[20:21], v[104:105], v[6:7] op_sel_hi:[1,0]
	v_mov_b32_e32 v10, v9
	v_pk_mul_f32 v[8:9], v[10:11], v[20:21]
	v_and_b32_sdwa v10, v14, v244 dst_sel:DWORD dst_unused:UNUSED_PAD src0_sel:WORD_1 src1_sel:DWORD
	v_add3_u32 v10, v14, v10, s33
	v_and_b32_sdwa v11, v9, v244 dst_sel:DWORD dst_unused:UNUSED_PAD src0_sel:WORD_1 src1_sel:DWORD
	v_and_b32_sdwa v14, v8, v244 dst_sel:DWORD dst_unused:UNUSED_PAD src0_sel:WORD_1 src1_sel:DWORD
	v_and_b32_sdwa v7, v15, v244 dst_sel:DWORD dst_unused:UNUSED_PAD src0_sel:WORD_1 src1_sel:DWORD
	v_add3_u32 v9, v9, v11, s33
	v_add3_u32 v8, v8, v14, s33
	v_add3_u32 v7, v15, v7, s33
	v_and_b32_e32 v9, 0xffff0000, v9
	v_and_b32_e32 v8, 0xffff0000, v8
	v_or_b32_sdwa v9, v9, v7 dst_sel:DWORD dst_unused:UNUSED_PAD src0_sel:DWORD src1_sel:WORD_1
	v_or_b32_sdwa v8, v8, v10 dst_sel:DWORD dst_unused:UNUSED_PAD src0_sel:DWORD src1_sel:WORD_1
	global_store_dwordx2 v[12:13], v[8:9], off offset:48
	v_pk_mul_f32 v[14:15], v[100:101], v[6:7] op_sel_hi:[1,0]
	s_waitcnt vmcnt(15)
	v_mov_b32_e32 v8, v224
	v_mov_b32_e32 v9, v225
	v_mov_b32_e32 v10, v226
	v_mov_b32_e32 v11, v227
	v_mov_b32_e32 v20, v8
	v_mov_b32_e32 v21, v10
	v_pk_mul_f32 v[14:15], v[20:21], v[14:15]
	v_pk_mul_f32 v[20:21], v[98:99], v[6:7] op_sel_hi:[1,0]
	v_mov_b32_e32 v10, v9
	v_pk_mul_f32 v[8:9], v[10:11], v[20:21]
	v_and_b32_sdwa v10, v14, v244 dst_sel:DWORD dst_unused:UNUSED_PAD src0_sel:WORD_1 src1_sel:DWORD
	v_add3_u32 v10, v14, v10, s33
	v_and_b32_sdwa v11, v9, v244 dst_sel:DWORD dst_unused:UNUSED_PAD src0_sel:WORD_1 src1_sel:DWORD
	v_and_b32_sdwa v14, v8, v244 dst_sel:DWORD dst_unused:UNUSED_PAD src0_sel:WORD_1 src1_sel:DWORD
	v_and_b32_sdwa v7, v15, v244 dst_sel:DWORD dst_unused:UNUSED_PAD src0_sel:WORD_1 src1_sel:DWORD
	v_add3_u32 v9, v9, v11, s33
	v_add3_u32 v8, v8, v14, s33
	v_add3_u32 v7, v15, v7, s33
	v_and_b32_e32 v9, 0xffff0000, v9
	v_and_b32_e32 v8, 0xffff0000, v8
	v_or_b32_sdwa v9, v9, v7 dst_sel:DWORD dst_unused:UNUSED_PAD src0_sel:DWORD src1_sel:WORD_1
	v_or_b32_sdwa v8, v8, v10 dst_sel:DWORD dst_unused:UNUSED_PAD src0_sel:DWORD src1_sel:WORD_1
	global_store_dwordx2 v[12:13], v[8:9], off offset:64
	v_pk_mul_f32 v[14:15], v[96:97], v[6:7] op_sel_hi:[1,0]
	s_waitcnt vmcnt(15)
	v_mov_b32_e32 v8, v228
	v_mov_b32_e32 v9, v229
	v_mov_b32_e32 v10, v230
	v_mov_b32_e32 v11, v231
	v_mov_b32_e32 v20, v8
	v_mov_b32_e32 v21, v10
	v_pk_mul_f32 v[14:15], v[20:21], v[14:15]
	v_pk_mul_f32 v[20:21], v[82:83], v[6:7] op_sel_hi:[1,0]
	v_mov_b32_e32 v10, v9
	v_pk_mul_f32 v[8:9], v[10:11], v[20:21]
	v_and_b32_sdwa v10, v14, v244 dst_sel:DWORD dst_unused:UNUSED_PAD src0_sel:WORD_1 src1_sel:DWORD
	v_add3_u32 v10, v14, v10, s33
	v_and_b32_sdwa v11, v9, v244 dst_sel:DWORD dst_unused:UNUSED_PAD src0_sel:WORD_1 src1_sel:DWORD
	v_and_b32_sdwa v14, v8, v244 dst_sel:DWORD dst_unused:UNUSED_PAD src0_sel:WORD_1 src1_sel:DWORD
	v_and_b32_sdwa v7, v15, v244 dst_sel:DWORD dst_unused:UNUSED_PAD src0_sel:WORD_1 src1_sel:DWORD
	v_add3_u32 v9, v9, v11, s33
	v_add3_u32 v8, v8, v14, s33
	v_add3_u32 v7, v15, v7, s33
	v_and_b32_e32 v9, 0xffff0000, v9
	v_and_b32_e32 v8, 0xffff0000, v8
	v_or_b32_sdwa v9, v9, v7 dst_sel:DWORD dst_unused:UNUSED_PAD src0_sel:DWORD src1_sel:WORD_1
	v_or_b32_sdwa v8, v8, v10 dst_sel:DWORD dst_unused:UNUSED_PAD src0_sel:DWORD src1_sel:WORD_1
	global_store_dwordx2 v[12:13], v[8:9], off offset:80
	v_pk_mul_f32 v[14:15], v[80:81], v[6:7] op_sel_hi:[1,0]
	s_waitcnt vmcnt(15)
	v_mov_b32_e32 v8, v232
	v_mov_b32_e32 v9, v233
	v_mov_b32_e32 v10, v234
	v_mov_b32_e32 v11, v235
	v_mov_b32_e32 v20, v8
	v_mov_b32_e32 v21, v10
	v_pk_mul_f32 v[14:15], v[20:21], v[14:15]
	v_pk_mul_f32 v[20:21], v[74:75], v[6:7] op_sel_hi:[1,0]
	v_mov_b32_e32 v10, v9
	v_pk_mul_f32 v[8:9], v[10:11], v[20:21]
	v_and_b32_sdwa v10, v14, v244 dst_sel:DWORD dst_unused:UNUSED_PAD src0_sel:WORD_1 src1_sel:DWORD
	v_add3_u32 v10, v14, v10, s33
	v_and_b32_sdwa v11, v9, v244 dst_sel:DWORD dst_unused:UNUSED_PAD src0_sel:WORD_1 src1_sel:DWORD
	v_and_b32_sdwa v14, v8, v244 dst_sel:DWORD dst_unused:UNUSED_PAD src0_sel:WORD_1 src1_sel:DWORD
	v_and_b32_sdwa v7, v15, v244 dst_sel:DWORD dst_unused:UNUSED_PAD src0_sel:WORD_1 src1_sel:DWORD
	v_add3_u32 v9, v9, v11, s33
	v_add3_u32 v8, v8, v14, s33
	v_add3_u32 v7, v15, v7, s33
	v_and_b32_e32 v9, 0xffff0000, v9
	v_and_b32_e32 v8, 0xffff0000, v8
	v_or_b32_sdwa v9, v9, v7 dst_sel:DWORD dst_unused:UNUSED_PAD src0_sel:DWORD src1_sel:WORD_1
	v_or_b32_sdwa v8, v8, v10 dst_sel:DWORD dst_unused:UNUSED_PAD src0_sel:DWORD src1_sel:WORD_1
	global_store_dwordx2 v[12:13], v[8:9], off offset:96
	v_pk_mul_f32 v[14:15], v[72:73], v[6:7] op_sel_hi:[1,0]
	s_waitcnt vmcnt(15)
	v_mov_b32_e32 v8, v236
	v_mov_b32_e32 v9, v237
	v_mov_b32_e32 v10, v238
	v_mov_b32_e32 v11, v239
	v_mov_b32_e32 v20, v8
	v_mov_b32_e32 v21, v10
	v_pk_mul_f32 v[14:15], v[20:21], v[14:15]
	v_pk_mul_f32 v[20:21], v[70:71], v[6:7] op_sel_hi:[1,0]
	v_mov_b32_e32 v10, v9
	v_pk_mul_f32 v[8:9], v[10:11], v[20:21]
	v_and_b32_sdwa v10, v14, v244 dst_sel:DWORD dst_unused:UNUSED_PAD src0_sel:WORD_1 src1_sel:DWORD
	v_add3_u32 v10, v14, v10, s33
	v_and_b32_sdwa v11, v9, v244 dst_sel:DWORD dst_unused:UNUSED_PAD src0_sel:WORD_1 src1_sel:DWORD
	v_and_b32_sdwa v14, v8, v244 dst_sel:DWORD dst_unused:UNUSED_PAD src0_sel:WORD_1 src1_sel:DWORD
	v_and_b32_sdwa v7, v15, v244 dst_sel:DWORD dst_unused:UNUSED_PAD src0_sel:WORD_1 src1_sel:DWORD
	v_add3_u32 v9, v9, v11, s33
	v_add3_u32 v8, v8, v14, s33
	v_add3_u32 v7, v15, v7, s33
	v_and_b32_e32 v9, 0xffff0000, v9
	v_and_b32_e32 v8, 0xffff0000, v8
	v_or_b32_sdwa v9, v9, v7 dst_sel:DWORD dst_unused:UNUSED_PAD src0_sel:DWORD src1_sel:WORD_1
	v_or_b32_sdwa v8, v8, v10 dst_sel:DWORD dst_unused:UNUSED_PAD src0_sel:DWORD src1_sel:WORD_1
	global_store_dwordx2 v[12:13], v[8:9], off offset:112
	v_pk_mul_f32 v[14:15], v[68:69], v[6:7] op_sel_hi:[1,0]
	s_waitcnt vmcnt(15)
; __device__ __forceinline__ unsigned pk2(float lo, float hi) { return f2bf(lo) | (f2bf(hi) << 16); }
; __device__ __forceinline__ void dattn_unit(LAS unsigned char* lds, int b, int h, int qb, const bf16* Q, const bf16* K, const bf16* V, bf16* YB, float lam, const float* subg, float oml, int tid) {
;     ...
;     for (int cb = 0; cb < 4; ++cb)
; #pragma unroll
;         for (int rg = 0; rg < 4; ++rg) { const int c = 32 * cb + 8 * rg + 4 * hi; const f32x4 g = *(const f32x4*)(subg + c);
;             v2u wv; wv.x = pk2(o[0][cb][4 * rg + 0] * rstd * g.x, o[0][cb][4 * rg + 1] * rstd * g.y); wv.y = pk2(o[0][cb][4 * rg + 2] * rstd * g.z, o[0][cb][4 * rg + 3] * rstd * g.w);
;             *(v2u*)(op + c) = wv; }
	v_mov_b32_e32 v8, v240
	v_mov_b32_e32 v9, v241
	v_mov_b32_e32 v10, v242
	v_mov_b32_e32 v11, v243
	v_mov_b32_e32 v20, v8
	v_mov_b32_e32 v21, v10
	v_pk_mul_f32 v[14:15], v[20:21], v[14:15]
	v_pk_mul_f32 v[20:21], v[66:67], v[6:7] op_sel_hi:[1,0]
	v_mov_b32_e32 v10, v9
	v_pk_mul_f32 v[8:9], v[10:11], v[20:21]
	v_and_b32_sdwa v10, v14, v244 dst_sel:DWORD dst_unused:UNUSED_PAD src0_sel:WORD_1 src1_sel:DWORD
	v_add3_u32 v10, v14, v10, s33
	v_and_b32_sdwa v11, v9, v244 dst_sel:DWORD dst_unused:UNUSED_PAD src0_sel:WORD_1 src1_sel:DWORD
	v_and_b32_sdwa v14, v8, v244 dst_sel:DWORD dst_unused:UNUSED_PAD src0_sel:WORD_1 src1_sel:DWORD
	v_and_b32_sdwa v7, v15, v244 dst_sel:DWORD dst_unused:UNUSED_PAD src0_sel:WORD_1 src1_sel:DWORD
	v_add3_u32 v9, v9, v11, s33
	v_add3_u32 v8, v8, v14, s33
	v_add3_u32 v7, v15, v7, s33
	v_and_b32_e32 v9, 0xffff0000, v9
	v_and_b32_e32 v8, 0xffff0000, v8
	v_or_b32_sdwa v9, v9, v7 dst_sel:DWORD dst_unused:UNUSED_PAD src0_sel:DWORD src1_sel:WORD_1
	v_or_b32_sdwa v8, v8, v10 dst_sel:DWORD dst_unused:UNUSED_PAD src0_sel:DWORD src1_sel:WORD_1
	global_store_dwordx2 v[12:13], v[8:9], off offset:128
	v_pk_mul_f32 v[14:15], v[64:65], v[6:7] op_sel_hi:[1,0]
	s_waitcnt vmcnt(15)
	v_mov_b32_e32 v8, v192
	v_mov_b32_e32 v9, v193
	v_mov_b32_e32 v10, v194
	v_mov_b32_e32 v11, v195
	v_mov_b32_e32 v20, v8
	v_mov_b32_e32 v21, v10
	v_pk_mul_f32 v[14:15], v[20:21], v[14:15]
	v_pk_mul_f32 v[20:21], v[50:51], v[6:7] op_sel_hi:[1,0]
	v_mov_b32_e32 v10, v9
	v_pk_mul_f32 v[8:9], v[10:11], v[20:21]
	v_and_b32_sdwa v10, v14, v244 dst_sel:DWORD dst_unused:UNUSED_PAD src0_sel:WORD_1 src1_sel:DWORD
	v_add3_u32 v10, v14, v10, s33
	v_and_b32_sdwa v11, v9, v244 dst_sel:DWORD dst_unused:UNUSED_PAD src0_sel:WORD_1 src1_sel:DWORD
	v_and_b32_sdwa v14, v8, v244 dst_sel:DWORD dst_unused:UNUSED_PAD src0_sel:WORD_1 src1_sel:DWORD
	v_and_b32_sdwa v7, v15, v244 dst_sel:DWORD dst_unused:UNUSED_PAD src0_sel:WORD_1 src1_sel:DWORD
	v_add3_u32 v9, v9, v11, s33
	v_add3_u32 v8, v8, v14, s33
	v_add3_u32 v7, v15, v7, s33
	v_and_b32_e32 v9, 0xffff0000, v9
	v_and_b32_e32 v8, 0xffff0000, v8
	v_or_b32_sdwa v9, v9, v7 dst_sel:DWORD dst_unused:UNUSED_PAD src0_sel:DWORD src1_sel:WORD_1
	v_or_b32_sdwa v8, v8, v10 dst_sel:DWORD dst_unused:UNUSED_PAD src0_sel:DWORD src1_sel:WORD_1
	global_store_dwordx2 v[12:13], v[8:9], off offset:144
	v_pk_mul_f32 v[14:15], v[48:49], v[6:7] op_sel_hi:[1,0]
	s_waitcnt vmcnt(15)
	v_mov_b32_e32 v8, v196
	v_mov_b32_e32 v9, v197
	v_mov_b32_e32 v10, v198
	v_mov_b32_e32 v11, v199
	v_mov_b32_e32 v20, v8
	v_mov_b32_e32 v21, v10
	v_pk_mul_f32 v[14:15], v[20:21], v[14:15]
	v_pk_mul_f32 v[20:21], v[38:39], v[6:7] op_sel_hi:[1,0]
	v_mov_b32_e32 v10, v9
	v_pk_mul_f32 v[8:9], v[10:11], v[20:21]
	v_and_b32_sdwa v10, v14, v244 dst_sel:DWORD dst_unused:UNUSED_PAD src0_sel:WORD_1 src1_sel:DWORD
	v_add3_u32 v10, v14, v10, s33
	v_and_b32_sdwa v11, v9, v244 dst_sel:DWORD dst_unused:UNUSED_PAD src0_sel:WORD_1 src1_sel:DWORD
	v_and_b32_sdwa v14, v8, v244 dst_sel:DWORD dst_unused:UNUSED_PAD src0_sel:WORD_1 src1_sel:DWORD
	v_and_b32_sdwa v7, v15, v244 dst_sel:DWORD dst_unused:UNUSED_PAD src0_sel:WORD_1 src1_sel:DWORD
	v_add3_u32 v9, v9, v11, s33
	v_add3_u32 v8, v8, v14, s33
	v_add3_u32 v7, v15, v7, s33
	v_and_b32_e32 v9, 0xffff0000, v9
	v_and_b32_e32 v8, 0xffff0000, v8
	v_or_b32_sdwa v9, v9, v7 dst_sel:DWORD dst_unused:UNUSED_PAD src0_sel:DWORD src1_sel:WORD_1
	v_or_b32_sdwa v8, v8, v10 dst_sel:DWORD dst_unused:UNUSED_PAD src0_sel:DWORD src1_sel:WORD_1
	global_store_dwordx2 v[12:13], v[8:9], off offset:160
	v_pk_mul_f32 v[14:15], v[36:37], v[6:7] op_sel_hi:[1,0]
	s_waitcnt vmcnt(15)
	v_mov_b32_e32 v8, v200
	v_mov_b32_e32 v9, v201
	v_mov_b32_e32 v10, v202
	v_mov_b32_e32 v11, v203
	v_mov_b32_e32 v20, v8
	v_mov_b32_e32 v21, v10
	v_pk_mul_f32 v[14:15], v[20:21], v[14:15]
	v_pk_mul_f32 v[20:21], v[34:35], v[6:7] op_sel_hi:[1,0]
	v_mov_b32_e32 v10, v9
	v_pk_mul_f32 v[8:9], v[10:11], v[20:21]
	v_and_b32_sdwa v10, v14, v244 dst_sel:DWORD dst_unused:UNUSED_PAD src0_sel:WORD_1 src1_sel:DWORD
	v_add3_u32 v10, v14, v10, s33
	v_and_b32_sdwa v11, v9, v244 dst_sel:DWORD dst_unused:UNUSED_PAD src0_sel:WORD_1 src1_sel:DWORD
	v_and_b32_sdwa v14, v8, v244 dst_sel:DWORD dst_unused:UNUSED_PAD src0_sel:WORD_1 src1_sel:DWORD
	v_and_b32_sdwa v7, v15, v244 dst_sel:DWORD dst_unused:UNUSED_PAD src0_sel:WORD_1 src1_sel:DWORD
	v_add3_u32 v9, v9, v11, s33
	v_add3_u32 v8, v8, v14, s33
	v_add3_u32 v7, v15, v7, s33
	v_and_b32_e32 v9, 0xffff0000, v9
	v_and_b32_e32 v8, 0xffff0000, v8
	v_or_b32_sdwa v9, v9, v7 dst_sel:DWORD dst_unused:UNUSED_PAD src0_sel:DWORD src1_sel:WORD_1
	v_or_b32_sdwa v8, v8, v10 dst_sel:DWORD dst_unused:UNUSED_PAD src0_sel:DWORD src1_sel:WORD_1
	global_store_dwordx2 v[12:13], v[8:9], off offset:176
	v_pk_mul_f32 v[14:15], v[32:33], v[6:7] op_sel_hi:[1,0]
	v_pk_mul_f32 v[18:19], v[18:19], v[6:7] op_sel_hi:[1,0]
	s_waitcnt vmcnt(15)
; __device__ __forceinline__ unsigned pk2(float lo, float hi) { return f2bf(lo) | (f2bf(hi) << 16); }
; __device__ __forceinline__ void dattn_unit(LAS unsigned char* lds, int b, int h, int qb, const bf16* Q, const bf16* K, const bf16* V, bf16* YB, float lam, const float* subg, float oml, int tid) {
;     ...
;     for (int cb = 0; cb < 4; ++cb)
; #pragma unroll
;         for (int rg = 0; rg < 4; ++rg) { const int c = 32 * cb + 8 * rg + 4 * hi; const f32x4 g = *(const f32x4*)(subg + c);
;             v2u wv; wv.x = pk2(o[0][cb][4 * rg + 0] * rstd * g.x, o[0][cb][4 * rg + 1] * rstd * g.y); wv.y = pk2(o[0][cb][4 * rg + 2] * rstd * g.z, o[0][cb][4 * rg + 3] * rstd * g.w);
;             *(v2u*)(op + c) = wv; }
; __device__ __forceinline__ void attn_super(LAS unsigned char* lds, int su, const bf16* Q, const bf16* K, const bf16* VA, bf16* YB, const float* tabg, float lam, const float* subg, float oml, int tid) {
;     ...
;     for (int qi = 0; qi < 4; ++qi) {
;         const int qb = (qi == 0) ? s : (qi == 1) ? 7 - s : (qi == 2) ? 8 + s : 15 - s;
;         dattn_unit(lds, b, h, qb, Q, K, VA, YB, lam, subg, oml, tid);
;     }
	v_mov_b32_e32 v8, v204
	v_mov_b32_e32 v9, v205
	v_mov_b32_e32 v10, v206
	v_mov_b32_e32 v11, v207
	v_mov_b32_e32 v20, v8
	v_mov_b32_e32 v21, v10
	v_pk_mul_f32 v[14:15], v[20:21], v[14:15]
	v_mov_b32_e32 v10, v9
	v_pk_mul_f32 v[8:9], v[10:11], v[18:19]
	v_and_b32_sdwa v10, v14, v244 dst_sel:DWORD dst_unused:UNUSED_PAD src0_sel:WORD_1 src1_sel:DWORD
	v_add3_u32 v10, v14, v10, s33
	v_and_b32_sdwa v11, v9, v244 dst_sel:DWORD dst_unused:UNUSED_PAD src0_sel:WORD_1 src1_sel:DWORD
	v_and_b32_sdwa v14, v8, v244 dst_sel:DWORD dst_unused:UNUSED_PAD src0_sel:WORD_1 src1_sel:DWORD
	v_and_b32_sdwa v7, v15, v244 dst_sel:DWORD dst_unused:UNUSED_PAD src0_sel:WORD_1 src1_sel:DWORD
	v_add3_u32 v9, v9, v11, s33
	v_add3_u32 v8, v8, v14, s33
	v_add3_u32 v7, v15, v7, s33
	v_and_b32_e32 v9, 0xffff0000, v9
	v_and_b32_e32 v8, 0xffff0000, v8
	v_or_b32_sdwa v9, v9, v7 dst_sel:DWORD dst_unused:UNUSED_PAD src0_sel:DWORD src1_sel:WORD_1
	v_or_b32_sdwa v8, v8, v10 dst_sel:DWORD dst_unused:UNUSED_PAD src0_sel:DWORD src1_sel:WORD_1
	global_store_dwordx2 v[12:13], v[8:9], off offset:192
	v_pk_mul_f32 v[14:15], v[16:17], v[6:7] op_sel_hi:[1,0]
	v_pk_mul_f32 v[4:5], v[4:5], v[6:7] op_sel_hi:[1,0]
	s_waitcnt vmcnt(15)
	v_mov_b32_e32 v8, v164
	v_mov_b32_e32 v9, v165
	v_mov_b32_e32 v10, v166
	v_mov_b32_e32 v11, v167
	v_mov_b32_e32 v17, v10
	v_mov_b32_e32 v10, v9
	v_mov_b32_e32 v16, v8
	v_pk_mul_f32 v[4:5], v[10:11], v[4:5]
	v_pk_mul_f32 v[14:15], v[16:17], v[14:15]
	v_and_b32_sdwa v9, v5, v244 dst_sel:DWORD dst_unused:UNUSED_PAD src0_sel:WORD_1 src1_sel:DWORD
	v_and_b32_sdwa v10, v4, v244 dst_sel:DWORD dst_unused:UNUSED_PAD src0_sel:WORD_1 src1_sel:DWORD
	v_and_b32_sdwa v7, v15, v244 dst_sel:DWORD dst_unused:UNUSED_PAD src0_sel:WORD_1 src1_sel:DWORD
	v_and_b32_sdwa v8, v14, v244 dst_sel:DWORD dst_unused:UNUSED_PAD src0_sel:WORD_1 src1_sel:DWORD
	v_add3_u32 v5, v5, v9, s33
	v_add3_u32 v4, v4, v10, s33
	v_add3_u32 v8, v14, v8, s33
	v_add3_u32 v7, v15, v7, s33
	v_and_b32_e32 v5, 0xffff0000, v5
	v_and_b32_e32 v4, 0xffff0000, v4
	v_or_b32_sdwa v5, v5, v7 dst_sel:DWORD dst_unused:UNUSED_PAD src0_sel:DWORD src1_sel:WORD_1
	v_or_b32_sdwa v4, v4, v8 dst_sel:DWORD dst_unused:UNUSED_PAD src0_sel:DWORD src1_sel:WORD_1
	global_store_dwordx2 v[12:13], v[4:5], off offset:208
	v_pk_mul_f32 v[2:3], v[2:3], v[6:7] op_sel_hi:[1,0]
	v_pk_mul_f32 v[0:1], v[0:1], v[6:7] op_sel_hi:[1,0]
	s_waitcnt vmcnt(15)
	v_mov_b32_e32 v8, v168
	v_mov_b32_e32 v9, v169
	v_mov_b32_e32 v10, v170
	v_mov_b32_e32 v11, v171
	v_mov_b32_e32 v4, v8
	v_mov_b32_e32 v5, v10
	v_pk_mul_f32 v[2:3], v[4:5], v[2:3]
	v_mov_b32_e32 v10, v9
	v_pk_mul_f32 v[0:1], v[10:11], v[0:1]
	v_and_b32_sdwa v4, v3, v244 dst_sel:DWORD dst_unused:UNUSED_PAD src0_sel:WORD_1 src1_sel:DWORD
	v_and_b32_sdwa v5, v2, v244 dst_sel:DWORD dst_unused:UNUSED_PAD src0_sel:WORD_1 src1_sel:DWORD
	v_add3_u32 v2, v2, v5, s33
	v_add3_u32 v3, v3, v4, s33
	v_and_b32_sdwa v4, v1, v244 dst_sel:DWORD dst_unused:UNUSED_PAD src0_sel:WORD_1 src1_sel:DWORD
	v_and_b32_sdwa v5, v0, v244 dst_sel:DWORD dst_unused:UNUSED_PAD src0_sel:WORD_1 src1_sel:DWORD
	v_add3_u32 v1, v1, v4, s33
	v_add3_u32 v0, v0, v5, s33
	v_and_b32_e32 v1, 0xffff0000, v1
	v_and_b32_e32 v0, 0xffff0000, v0
	v_or_b32_sdwa v1, v1, v3 dst_sel:DWORD dst_unused:UNUSED_PAD src0_sel:DWORD src1_sel:WORD_1
	v_or_b32_sdwa v0, v0, v2 dst_sel:DWORD dst_unused:UNUSED_PAD src0_sel:DWORD src1_sel:WORD_1
	global_store_dwordx2 v[12:13], v[0:1], off offset:224
	v_mov_b32_e32 v4, v28
	v_mov_b32_e32 v5, v30
	v_pk_mul_f32 v[4:5], v[4:5], v[6:7] op_sel_hi:[1,0]
	v_mov_b32_e32 v30, v29
	v_pk_mul_f32 v[6:7], v[30:31], v[6:7] op_sel_hi:[1,0]
	s_waitcnt vmcnt(15)
	v_mov_b32_e32 v0, v172
	v_mov_b32_e32 v1, v173
	v_mov_b32_e32 v2, v174
	v_mov_b32_e32 v3, v175
	v_mov_b32_e32 v8, v0
	v_mov_b32_e32 v9, v2
	v_pk_mul_f32 v[4:5], v[8:9], v[4:5]
	v_mov_b32_e32 v2, v1
	v_pk_mul_f32 v[0:1], v[2:3], v[6:7]
	v_and_b32_sdwa v2, v5, v244 dst_sel:DWORD dst_unused:UNUSED_PAD src0_sel:WORD_1 src1_sel:DWORD
	v_and_b32_sdwa v3, v4, v244 dst_sel:DWORD dst_unused:UNUSED_PAD src0_sel:WORD_1 src1_sel:DWORD
	v_add3_u32 v3, v4, v3, s33
	v_add3_u32 v2, v5, v2, s33
	v_and_b32_sdwa v4, v1, v244 dst_sel:DWORD dst_unused:UNUSED_PAD src0_sel:WORD_1 src1_sel:DWORD
	v_and_b32_sdwa v5, v0, v244 dst_sel:DWORD dst_unused:UNUSED_PAD src0_sel:WORD_1 src1_sel:DWORD
	v_add3_u32 v1, v1, v4, s33
	v_add3_u32 v0, v0, v5, s33
	v_and_b32_e32 v1, 0xffff0000, v1
	v_and_b32_e32 v0, 0xffff0000, v0
	v_or_b32_sdwa v1, v1, v2 dst_sel:DWORD dst_unused:UNUSED_PAD src0_sel:DWORD src1_sel:WORD_1
	v_or_b32_sdwa v0, v0, v3 dst_sel:DWORD dst_unused:UNUSED_PAD src0_sel:DWORD src1_sel:WORD_1
	global_store_dwordx2 v[12:13], v[0:1], off offset:240
	s_cbranch_scc0 .LBB0_213
